# indexer score loop: key-fragment prefetch as global loads with counted vmcnt so it overlaps the MFMA/VALU of the current group (was drained by vmcnt(0) right after issue)
# speedup vs baseline: 1.0045x; 1.0045x over previous
; #define LAS __attribute__((address_space(3)))
; DI int fresh_tid() { int t = threadIdx.x; asm volatile("" : "+v"(t)); return t; }
; #define IDX_LOADG(dst, grp_) do { _Pragma("unroll") for (int tt = 0; tt < 4; ++tt) { const bf16_t* p_ = ikl + (size_t)(64 * (grp_) + 16 * tt) * 64; dst[tt][0] = *(const bf16x8*)p_; dst[tt][1] = *(const bf16x8*)(p_ + 32); } } while (0)
; DI void idx_rows(LAS unsigned char* lds, int b, int tg, const bf16_t* IQ, const bf16_t* IK, const float* IW, unsigned long long* maskT) {
;     const int tid = fresh_tid(), lane = tid & 63, wave = __builtin_amdgcn_readfirstlane(tid >> 6);
;     const int g = lane >> 4, c16 = lane & 15;
;     const int tb = tg * 8; const size_t rowb = (size_t)b * S_ + tb;
;     const int ngrp = (tb + 7) / 64 + 1;
;     LAS unsigned* stab = (LAS unsigned*)lds;
;     {
;         bf16x8 a0[8], a1[8]; f32x4 wv[8];
; #pragma unroll
;         for (int j = 0; j < 8; ++j) {
;             a0[j] = *(const bf16x8*)(IQ + (rowb + j) * 1024 + c16 * 64 + g * 8);
;             a1[j] = *(const bf16x8*)(IQ + (rowb + j) * 1024 + c16 * 64 + 32 + g * 8);
;             wv[j] = *(const f32x4*)(IW + (rowb + j) * 16 + 4 * g);
;         }
;         const bf16_t* ikl = IK + (size_t)b * S_ * 64 + c16 * 64 + g * 8;
;         bf16x8 bA[4][2], bB[4][2];
;     ...
;         __syncthreads();
;         if (wave < ngrp) IDX_LOADG(bA, wave);
.LBB0_619:
	s_or_b64 exec, exec, s[0:1]
	s_lshr_b32 s0, s2, 2
	v_mov_b32_e32 v96, v186
	s_and_b32 s29, s2, 3
	s_sub_i32 s0, 0x1ff, s0
	s_lshl_b32 s1, s0, 3
	v_lshlrev_b32_e32 v0, 6, v96
	s_lshl_b32 s3, s29, 12
	v_and_b32_e32 v0, 0x3c0, v0
	s_or_b32 s3, s3, s1
	v_lshlrev_b32_e32 v160, 1, v0
	v_lshl_add_u64 v[80:81], s[46:47], 0, v[160:161]
	v_and_b32_e32 v82, 48, v96
	v_mov_b32_e32 v83, v161
	s_lshl_b32 s70, s3, 11
	v_lshl_add_u64 v[88:89], s[48:49], 0, v[82:83]
	v_lshl_add_u64 v[0:1], v[80:81], 0, s[70:71]
	s_lshl_b32 s70, s3, 6
	s_or_b32 s4, s3, 1
	v_lshl_add_u64 v[8:9], v[88:89], 0, s[70:71]
	s_lshl_b32 s70, s4, 11
	v_lshl_add_u64 v[10:11], v[80:81], 0, s[70:71]
	s_lshl_b32 s70, s4, 6
	s_or_b32 s4, s3, 2
	v_lshl_add_u64 v[20:21], v[88:89], 0, s[70:71]
	s_lshl_b32 s70, s4, 11
	v_lshl_add_u64 v[24:25], v[80:81], 0, s[70:71]
	s_lshl_b32 s70, s4, 6
	s_or_b32 s4, s3, 3
	v_lshl_add_u64 v[32:33], v[88:89], 0, s[70:71]
	s_lshl_b32 s70, s4, 11
	v_lshl_add_u64 v[34:35], v[80:81], 0, s[70:71]
	s_lshl_b32 s70, s4, 6
	s_or_b32 s4, s3, 4
	v_lshl_add_u64 v[44:45], v[88:89], 0, s[70:71]
	s_lshl_b32 s70, s4, 11
	v_lshl_add_u64 v[48:49], v[80:81], 0, s[70:71]
	s_lshl_b32 s70, s4, 6
	s_or_b32 s4, s3, 5
	v_lshl_add_u64 v[56:57], v[88:89], 0, s[70:71]
	s_lshl_b32 s70, s4, 11
	v_lshl_add_u64 v[58:59], v[80:81], 0, s[70:71]
	s_lshl_b32 s70, s4, 6
	s_or_b32 s4, s3, 6
	v_lshl_add_u64 v[68:69], v[88:89], 0, s[70:71]
	s_lshl_b32 s70, s4, 11
	v_lshl_add_u64 v[72:73], v[80:81], 0, s[70:71]
	s_lshl_b32 s70, s4, 6
	s_or_b32 s3, s3, 7
	v_lshl_add_u64 v[84:85], v[88:89], 0, s[70:71]
	s_lshl_b32 s70, s3, 11
	v_lshl_add_u64 v[80:81], v[80:81], 0, s[70:71]
	s_lshl_b32 s70, s3, 6
	v_lshl_add_u64 v[4:5], v[0:1], 0, v[82:83]
	v_lshl_add_u64 v[16:17], v[10:11], 0, v[82:83]
	v_lshl_add_u64 v[28:29], v[24:25], 0, v[82:83]
	v_lshl_add_u64 v[40:41], v[34:35], 0, v[82:83]
	v_lshl_add_u64 v[52:53], v[48:49], 0, v[82:83]
	v_lshl_add_u64 v[64:65], v[58:59], 0, v[82:83]
	v_lshl_add_u64 v[76:77], v[72:73], 0, v[82:83]
	v_lshl_add_u64 v[90:91], v[80:81], 0, v[82:83]
	v_lshl_add_u64 v[92:93], v[88:89], 0, s[70:71]
	global_load_dwordx4 v[0:3], v[4:5], off
	s_nop 0
	global_load_dwordx4 v[4:7], v[4:5], off offset:64
	s_nop 0
	global_load_dwordx4 v[8:11], v[8:9], off
	s_nop 0
	global_load_dwordx4 v[12:15], v[16:17], off
	s_nop 0
	global_load_dwordx4 v[16:19], v[16:17], off offset:64
	s_nop 0
	global_load_dwordx4 v[20:23], v[20:21], off
	s_nop 0
	global_load_dwordx4 v[24:27], v[28:29], off
	s_nop 0
	global_load_dwordx4 v[28:31], v[28:29], off offset:64
	s_nop 0
	global_load_dwordx4 v[32:35], v[32:33], off
	s_nop 0
	global_load_dwordx4 v[36:39], v[40:41], off
	s_nop 0
	global_load_dwordx4 v[40:43], v[40:41], off offset:64
	s_nop 0
	global_load_dwordx4 v[44:47], v[44:45], off
	s_nop 0
	global_load_dwordx4 v[48:51], v[52:53], off
	s_nop 0
	global_load_dwordx4 v[52:55], v[52:53], off offset:64
	s_nop 0
	global_load_dwordx4 v[56:59], v[56:57], off
	s_nop 0
	global_load_dwordx4 v[60:63], v[64:65], off
	s_nop 0
	global_load_dwordx4 v[64:67], v[64:65], off offset:64
	s_nop 0
	global_load_dwordx4 v[68:71], v[68:69], off
	s_nop 0
	global_load_dwordx4 v[72:75], v[76:77], off
	s_nop 0
	global_load_dwordx4 v[76:79], v[76:77], off offset:64
	s_nop 0
	global_load_dwordx4 v[80:83], v[84:85], off
	s_nop 0
	global_load_dwordx4 v[84:87], v[90:91], off
	s_nop 0
	global_load_dwordx4 v[88:91], v[90:91], off offset:64
	s_nop 0
	global_load_dwordx4 v[92:95], v[92:93], off
	v_readfirstlane_b32 s4, v96
	s_ashr_i32 s3, s4, 6
	s_lshr_b32 s0, s0, 3
	v_and_b32_e32 v174, 63, v96
	s_cmp_gt_i32 s3, s0
	s_waitcnt lgkmcnt(0)
	s_barrier
	s_cbranch_scc1 .LBB0_628
	s_lshl_b32 s5, s29, 19
	v_readlane_b32 s6, v255, 30
	v_lshrrev_b32_e32 v96, 1, v96
	s_add_u32 s6, s6, s5
	v_readlane_b32 s5, v255, 31
	v_and_b32_e32 v98, 24, v96
	s_addc_u32 s7, s5, 0
	s_andn2_b32 s4, s4, 63
	v_lshl_add_u64 v[96:97], s[6:7], 0, v[160:161]
	v_lshlrev_b32_e32 v160, 1, v98
	s_ashr_i32 s5, s4, 31
	v_lshl_add_u64 v[172:173], v[96:97], 0, v[160:161]
	s_lshl_b64 s[6:7], s[4:5], 7
	v_lshl_add_u64 v[100:101], v[172:173], 0, s[6:7]
	s_or_b32 s6, s4, 16
	s_ashr_i32 s7, s6, 31
	s_lshl_b64 s[6:7], s[6:7], 7
	v_lshl_add_u64 v[108:109], v[172:173], 0, s[6:7]
	s_or_b32 s6, s4, 32
	s_or_b32 s4, s4, 48
	s_ashr_i32 s7, s6, 31
	s_ashr_i32 s5, s4, 31
	s_lshl_b64 s[6:7], s[6:7], 7
	s_lshl_b64 s[4:5], s[4:5], 7
	v_lshl_add_u64 v[116:117], v[172:173], 0, s[6:7]
	v_lshl_add_u64 v[124:125], v[172:173], 0, s[4:5]
	global_load_dwordx4 v[96:99], v[100:101], off
	s_nop 0
	global_load_dwordx4 v[100:103], v[100:101], off offset:64
	s_nop 0
	global_load_dwordx4 v[104:107], v[108:109], off
	s_nop 0
	global_load_dwordx4 v[108:111], v[108:109], off offset:64
	s_nop 0
	global_load_dwordx4 v[112:115], v[116:117], off
	s_nop 0
	global_load_dwordx4 v[116:119], v[116:117], off offset:64
	s_nop 0
	global_load_dwordx4 v[120:123], v[124:125], off
	s_nop 0
	global_load_dwordx4 v[124:127], v[124:125], off offset:64
	s_lshl_b32 s7, s3, 8
	s_add_i32 s7, s7, 0
	s_lshl_b32 s6, s3, 6
	s_add_i32 s7, s7, 0x10000
	s_or_b32 s4, s1, 1
	s_or_b32 s5, s1, 2
	s_or_b32 s10, s1, 3
	s_or_b32 s11, s1, 4
	s_or_b32 s12, s1, 5
	s_or_b32 s13, s1, 6
	s_or_b32 s14, s1, 7
	s_addk_i32 s6, 0x430
	v_lshl_add_u32 v160, v174, 2, s7
	s_mov_b32 s15, s3
	s_branch .LBB0_623
.LBB0_621:
	s_waitcnt vmcnt(0)
.Lidx_c2:
	v_mfma_f32_16x16x32_bf16 v[176:179], v[0:3], v[132:135], 0
	v_add_u32_e32 v175, 0xfffffdd0, v175
	v_cmp_ge_i32_e32 vcc, s1, v175
	v_add_u32_e32 v166, 0xffff0800, v160
	v_mfma_f32_16x16x32_bf16 v[180:183], v[0:3], v[140:143], 0
	v_mfma_f32_16x16x32_bf16 v[194:197], v[0:3], v[148:151], 0
	v_mfma_f32_16x16x32_bf16 v[198:201], v[0:3], v[156:159], 0
	v_mfma_f32_16x16x32_bf16 v[176:179], v[4:7], v[128:131], v[176:179]
	v_mfma_f32_16x16x32_bf16 v[180:183], v[4:7], v[136:139], v[180:183]
	v_mfma_f32_16x16x32_bf16 v[194:197], v[4:7], v[144:147], v[194:197]
	s_nop 5
	v_max_i32_e32 v178, 0, v178
	v_max_i32_e32 v179, 0, v179
	v_max_i32_e32 v176, 0, v176
	v_mfma_f32_16x16x32_bf16 v[198:201], v[4:7], v[152:155], v[198:201]
	v_max_i32_e32 v177, 0, v177
	v_pk_mul_f32 v[178:179], v[10:11], v[178:179]
	s_nop 0
	v_pk_fma_f32 v[176:177], v[8:9], v[176:177], v[178:179]
	v_max_i32_e32 v178, 0, v180
	v_max_i32_e32 v179, 0, v181
	v_max_i32_e32 v180, 0, v182
	v_max_i32_e32 v181, 0, v183
	v_pk_mul_f32 v[180:181], v[10:11], v[180:181]
	v_max_i32_e32 v182, 0, v196
	v_max_i32_e32 v183, 0, v197
	v_pk_fma_f32 v[178:179], v[8:9], v[178:179], v[180:181]
	v_max_i32_e32 v180, 0, v194
	v_max_i32_e32 v181, 0, v195
	v_pk_mul_f32 v[182:183], v[10:11], v[182:183]
	v_max_i32_e32 v184, 0, v200
	v_max_i32_e32 v185, 0, v201
	v_pk_add_f32 v[176:177], v[176:177], v[176:177] op_sel:[0,1] op_sel_hi:[1,0]
	v_pk_add_f32 v[178:179], v[178:179], v[178:179] op_sel:[0,1] op_sel_hi:[1,0]
	v_pk_fma_f32 v[180:181], v[8:9], v[180:181], v[182:183]
	v_max_i32_e32 v182, 0, v198
	v_max_i32_e32 v183, 0, v199
	v_pk_mul_f32 v[184:185], v[10:11], v[184:185]
	v_permlane16_swap_b32_e32 v176, v178
	v_pk_fma_f32 v[182:183], v[8:9], v[182:183], v[184:185]
	v_pk_add_f32 v[180:181], v[180:181], v[180:181] op_sel:[0,1] op_sel_hi:[1,0]
	v_pk_add_f32 v[182:183], v[182:183], v[182:183] op_sel:[0,1] op_sel_hi:[1,0]
	v_add_f32_e32 v167, v176, v178
	v_mfma_f32_16x16x32_bf16 v[176:179], v[12:15], v[132:135], 0
	v_permlane16_swap_b32_e32 v180, v182
	v_add_f32_e32 v168, v180, v182
	v_mfma_f32_16x16x32_bf16 v[180:183], v[12:15], v[140:143], 0
	s_nop 0
	v_permlane32_swap_b32_e32 v167, v168
	v_add_f32_e32 v167, v167, v168
	v_mfma_f32_16x16x32_bf16 v[194:197], v[12:15], v[148:151], 0
	v_ashrrev_i32_e32 v168, 31, v167
	v_bitop3_b32 v167, v168, v167, s33 bitop3:0x36
	v_cndmask_b32_e32 v167, 0, v167, vcc
	v_mfma_f32_16x16x32_bf16 v[198:201], v[12:15], v[156:159], 0
	ds_write_b32 v166, v167
	v_cmp_ge_i32_e32 vcc, s4, v175
	v_mfma_f32_16x16x32_bf16 v[176:179], v[16:19], v[128:131], v[176:179]
	v_mfma_f32_16x16x32_bf16 v[180:183], v[16:19], v[136:139], v[180:183]
	v_mfma_f32_16x16x32_bf16 v[194:197], v[16:19], v[144:147], v[194:197]
	s_nop 5
	v_max_i32_e32 v178, 0, v178
	v_max_i32_e32 v179, 0, v179
	v_max_i32_e32 v176, 0, v176
	v_mfma_f32_16x16x32_bf16 v[198:201], v[16:19], v[152:155], v[198:201]
	v_max_i32_e32 v177, 0, v177
	v_pk_mul_f32 v[178:179], v[22:23], v[178:179]
	s_nop 0
	v_pk_fma_f32 v[176:177], v[20:21], v[176:177], v[178:179]
	v_max_i32_e32 v178, 0, v180
	v_max_i32_e32 v179, 0, v181
	v_max_i32_e32 v180, 0, v182
	v_max_i32_e32 v181, 0, v183
	v_pk_mul_f32 v[180:181], v[22:23], v[180:181]
	v_max_i32_e32 v182, 0, v196
	v_max_i32_e32 v183, 0, v197
	v_pk_fma_f32 v[178:179], v[20:21], v[178:179], v[180:181]
	v_max_i32_e32 v180, 0, v194
	v_max_i32_e32 v181, 0, v195
	v_pk_mul_f32 v[182:183], v[22:23], v[182:183]
	v_max_i32_e32 v184, 0, v200
	v_max_i32_e32 v185, 0, v201
	v_pk_add_f32 v[176:177], v[176:177], v[176:177] op_sel:[0,1] op_sel_hi:[1,0]
	v_pk_add_f32 v[178:179], v[178:179], v[178:179] op_sel:[0,1] op_sel_hi:[1,0]
	v_pk_fma_f32 v[180:181], v[20:21], v[180:181], v[182:183]
	v_max_i32_e32 v182, 0, v198
	v_max_i32_e32 v183, 0, v199
	v_pk_mul_f32 v[184:185], v[22:23], v[184:185]
	v_permlane16_swap_b32_e32 v176, v178
	v_pk_fma_f32 v[182:183], v[20:21], v[182:183], v[184:185]
	v_pk_add_f32 v[180:181], v[180:181], v[180:181] op_sel:[0,1] op_sel_hi:[1,0]
	v_pk_add_f32 v[182:183], v[182:183], v[182:183] op_sel:[0,1] op_sel_hi:[1,0]
	v_add_f32_e32 v166, v176, v178
	v_mfma_f32_16x16x32_bf16 v[176:179], v[24:27], v[132:135], 0
	v_permlane16_swap_b32_e32 v180, v182
	v_add_f32_e32 v167, v180, v182
	v_mfma_f32_16x16x32_bf16 v[180:183], v[24:27], v[140:143], 0
	s_nop 0
	v_permlane32_swap_b32_e32 v166, v167
	v_add_f32_e32 v166, v166, v167
	v_mfma_f32_16x16x32_bf16 v[194:197], v[24:27], v[148:151], 0
	v_ashrrev_i32_e32 v167, 31, v166
	v_bitop3_b32 v166, v167, v166, s33 bitop3:0x36
	v_cndmask_b32_e32 v166, 0, v166, vcc
	v_mfma_f32_16x16x32_bf16 v[198:201], v[24:27], v[156:159], 0
	v_add_u32_e32 v167, 0xffff4800, v160
	ds_write_b32 v167, v166
	v_cmp_ge_i32_e32 vcc, s5, v175
	v_mfma_f32_16x16x32_bf16 v[176:179], v[28:31], v[128:131], v[176:179]
	v_mfma_f32_16x16x32_bf16 v[180:183], v[28:31], v[136:139], v[180:183]
	v_mfma_f32_16x16x32_bf16 v[194:197], v[28:31], v[144:147], v[194:197]
	s_nop 5
	v_max_i32_e32 v178, 0, v178
	v_max_i32_e32 v179, 0, v179
	v_max_i32_e32 v176, 0, v176
	v_mfma_f32_16x16x32_bf16 v[198:201], v[28:31], v[152:155], v[198:201]
	v_max_i32_e32 v177, 0, v177
	v_pk_mul_f32 v[178:179], v[34:35], v[178:179]
	s_nop 0
	v_pk_fma_f32 v[176:177], v[32:33], v[176:177], v[178:179]
	v_max_i32_e32 v178, 0, v180
	v_max_i32_e32 v179, 0, v181
	v_max_i32_e32 v180, 0, v182
	v_max_i32_e32 v181, 0, v183
	v_pk_mul_f32 v[180:181], v[34:35], v[180:181]
	v_max_i32_e32 v182, 0, v196
	v_max_i32_e32 v183, 0, v197
	v_pk_fma_f32 v[178:179], v[32:33], v[178:179], v[180:181]
	v_max_i32_e32 v180, 0, v194
	v_max_i32_e32 v181, 0, v195
	v_pk_mul_f32 v[182:183], v[34:35], v[182:183]
	v_max_i32_e32 v184, 0, v200
	v_max_i32_e32 v185, 0, v201
	v_pk_add_f32 v[176:177], v[176:177], v[176:177] op_sel:[0,1] op_sel_hi:[1,0]
	v_pk_add_f32 v[178:179], v[178:179], v[178:179] op_sel:[0,1] op_sel_hi:[1,0]
	v_pk_fma_f32 v[180:181], v[32:33], v[180:181], v[182:183]
	v_max_i32_e32 v182, 0, v198
	v_max_i32_e32 v183, 0, v199
	v_pk_mul_f32 v[184:185], v[34:35], v[184:185]
	v_permlane16_swap_b32_e32 v176, v178
	v_pk_fma_f32 v[182:183], v[32:33], v[182:183], v[184:185]
	v_pk_add_f32 v[180:181], v[180:181], v[180:181] op_sel:[0,1] op_sel_hi:[1,0]
	v_pk_add_f32 v[182:183], v[182:183], v[182:183] op_sel:[0,1] op_sel_hi:[1,0]
	v_add_f32_e32 v166, v176, v178
	v_mfma_f32_16x16x32_bf16 v[176:179], v[36:39], v[132:135], 0
	v_permlane16_swap_b32_e32 v180, v182
	v_add_f32_e32 v167, v180, v182
	v_mfma_f32_16x16x32_bf16 v[180:183], v[36:39], v[140:143], 0
	s_nop 0
	v_permlane32_swap_b32_e32 v166, v167
	v_add_f32_e32 v166, v166, v167
	v_mfma_f32_16x16x32_bf16 v[194:197], v[36:39], v[148:151], 0
	v_ashrrev_i32_e32 v167, 31, v166
	v_bitop3_b32 v166, v167, v166, s33 bitop3:0x36
	v_cndmask_b32_e32 v166, 0, v166, vcc
	v_mfma_f32_16x16x32_bf16 v[198:201], v[36:39], v[156:159], 0
	v_add_u32_e32 v167, 0xffff8800, v160
	ds_write_b32 v167, v166
	v_cmp_ge_i32_e32 vcc, s10, v175
	v_mfma_f32_16x16x32_bf16 v[176:179], v[40:43], v[128:131], v[176:179]
	v_mfma_f32_16x16x32_bf16 v[180:183], v[40:43], v[136:139], v[180:183]
	v_mfma_f32_16x16x32_bf16 v[194:197], v[40:43], v[144:147], v[194:197]
	s_nop 5
	v_max_i32_e32 v178, 0, v178
	v_max_i32_e32 v179, 0, v179
	v_max_i32_e32 v176, 0, v176
	v_mfma_f32_16x16x32_bf16 v[198:201], v[40:43], v[152:155], v[198:201]
	v_max_i32_e32 v177, 0, v177
	v_pk_mul_f32 v[178:179], v[46:47], v[178:179]
	s_nop 0
	v_pk_fma_f32 v[176:177], v[44:45], v[176:177], v[178:179]
	v_max_i32_e32 v178, 0, v180
	v_max_i32_e32 v179, 0, v181
	v_max_i32_e32 v180, 0, v182
	v_max_i32_e32 v181, 0, v183
	v_pk_mul_f32 v[180:181], v[46:47], v[180:181]
	v_max_i32_e32 v182, 0, v196
	v_max_i32_e32 v183, 0, v197
	v_pk_fma_f32 v[178:179], v[44:45], v[178:179], v[180:181]
	v_max_i32_e32 v180, 0, v194
	v_max_i32_e32 v181, 0, v195
	v_pk_mul_f32 v[182:183], v[46:47], v[182:183]
	v_max_i32_e32 v184, 0, v200
	v_max_i32_e32 v185, 0, v201
	v_pk_add_f32 v[176:177], v[176:177], v[176:177] op_sel:[0,1] op_sel_hi:[1,0]
	v_pk_add_f32 v[178:179], v[178:179], v[178:179] op_sel:[0,1] op_sel_hi:[1,0]
	v_pk_fma_f32 v[180:181], v[44:45], v[180:181], v[182:183]
	v_max_i32_e32 v182, 0, v198
	v_max_i32_e32 v183, 0, v199
	v_pk_mul_f32 v[184:185], v[46:47], v[184:185]
	v_permlane16_swap_b32_e32 v176, v178
	v_pk_fma_f32 v[182:183], v[44:45], v[182:183], v[184:185]
	v_pk_add_f32 v[180:181], v[180:181], v[180:181] op_sel:[0,1] op_sel_hi:[1,0]
	v_pk_add_f32 v[182:183], v[182:183], v[182:183] op_sel:[0,1] op_sel_hi:[1,0]
	v_add_f32_e32 v166, v176, v178
	v_mfma_f32_16x16x32_bf16 v[176:179], v[48:51], v[132:135], 0
	v_permlane16_swap_b32_e32 v180, v182
	v_add_f32_e32 v167, v180, v182
	v_mfma_f32_16x16x32_bf16 v[180:183], v[48:51], v[140:143], 0
	s_nop 0
	v_permlane32_swap_b32_e32 v166, v167
	v_add_f32_e32 v166, v166, v167
	v_mfma_f32_16x16x32_bf16 v[194:197], v[48:51], v[148:151], 0
	v_ashrrev_i32_e32 v167, 31, v166
	v_bitop3_b32 v166, v167, v166, s33 bitop3:0x36
	v_cndmask_b32_e32 v166, 0, v166, vcc
	v_mfma_f32_16x16x32_bf16 v[198:201], v[48:51], v[156:159], 0
	v_add_u32_e32 v167, 0xffffc800, v160
	ds_write_b32 v167, v166
	v_cmp_ge_i32_e32 vcc, s11, v175
	v_mfma_f32_16x16x32_bf16 v[176:179], v[52:55], v[128:131], v[176:179]
	v_mfma_f32_16x16x32_bf16 v[180:183], v[52:55], v[136:139], v[180:183]
	v_mfma_f32_16x16x32_bf16 v[194:197], v[52:55], v[144:147], v[194:197]
	s_nop 5
	v_max_i32_e32 v178, 0, v178
	v_max_i32_e32 v179, 0, v179
	v_max_i32_e32 v176, 0, v176
	v_mfma_f32_16x16x32_bf16 v[198:201], v[52:55], v[152:155], v[198:201]
	v_max_i32_e32 v177, 0, v177
	v_pk_mul_f32 v[178:179], v[58:59], v[178:179]
	s_nop 0
	v_pk_fma_f32 v[176:177], v[56:57], v[176:177], v[178:179]
	v_max_i32_e32 v178, 0, v180
	v_max_i32_e32 v179, 0, v181
	v_max_i32_e32 v180, 0, v182
	v_max_i32_e32 v181, 0, v183
	v_pk_mul_f32 v[180:181], v[58:59], v[180:181]
	v_max_i32_e32 v182, 0, v196
	v_max_i32_e32 v183, 0, v197
	v_pk_fma_f32 v[178:179], v[56:57], v[178:179], v[180:181]
	v_max_i32_e32 v180, 0, v194
	v_max_i32_e32 v181, 0, v195
	v_pk_mul_f32 v[182:183], v[58:59], v[182:183]
	v_max_i32_e32 v184, 0, v200
	v_max_i32_e32 v185, 0, v201
	v_pk_add_f32 v[176:177], v[176:177], v[176:177] op_sel:[0,1] op_sel_hi:[1,0]
	v_pk_add_f32 v[178:179], v[178:179], v[178:179] op_sel:[0,1] op_sel_hi:[1,0]
	v_pk_fma_f32 v[180:181], v[56:57], v[180:181], v[182:183]
	v_max_i32_e32 v182, 0, v198
	v_max_i32_e32 v183, 0, v199
	v_pk_mul_f32 v[184:185], v[58:59], v[184:185]
	v_permlane16_swap_b32_e32 v176, v178
	v_pk_fma_f32 v[182:183], v[56:57], v[182:183], v[184:185]
	v_pk_add_f32 v[180:181], v[180:181], v[180:181] op_sel:[0,1] op_sel_hi:[1,0]
	v_pk_add_f32 v[182:183], v[182:183], v[182:183] op_sel:[0,1] op_sel_hi:[1,0]
	v_add_f32_e32 v166, v176, v178
	v_mfma_f32_16x16x32_bf16 v[176:179], v[60:63], v[132:135], 0
	v_permlane16_swap_b32_e32 v180, v182
	v_add_f32_e32 v167, v180, v182
	v_mfma_f32_16x16x32_bf16 v[180:183], v[60:63], v[140:143], 0
	s_nop 0
	v_permlane32_swap_b32_e32 v166, v167
	v_add_f32_e32 v166, v166, v167
	v_mfma_f32_16x16x32_bf16 v[194:197], v[60:63], v[148:151], 0
	v_ashrrev_i32_e32 v167, 31, v166
	v_bitop3_b32 v166, v167, v166, s33 bitop3:0x36
	v_cndmask_b32_e32 v166, 0, v166, vcc
	v_mfma_f32_16x16x32_bf16 v[198:201], v[60:63], v[156:159], 0
	v_cmp_ge_i32_e32 vcc, s12, v175
	v_mfma_f32_16x16x32_bf16 v[176:179], v[64:67], v[128:131], v[176:179]
	v_mfma_f32_16x16x32_bf16 v[180:183], v[64:67], v[136:139], v[180:183]
	v_mfma_f32_16x16x32_bf16 v[194:197], v[64:67], v[144:147], v[194:197]
	s_nop 5
	v_max_i32_e32 v178, 0, v178
	v_max_i32_e32 v179, 0, v179
	v_max_i32_e32 v176, 0, v176
	v_mfma_f32_16x16x32_bf16 v[198:201], v[64:67], v[152:155], v[198:201]
	v_max_i32_e32 v177, 0, v177
	v_pk_mul_f32 v[178:179], v[70:71], v[178:179]
	s_nop 0
	v_pk_fma_f32 v[176:177], v[68:69], v[176:177], v[178:179]
	v_max_i32_e32 v178, 0, v180
	v_max_i32_e32 v179, 0, v181
	v_max_i32_e32 v180, 0, v182
	v_max_i32_e32 v181, 0, v183
	v_pk_mul_f32 v[180:181], v[70:71], v[180:181]
	v_max_i32_e32 v182, 0, v196
	v_max_i32_e32 v183, 0, v197
	v_pk_fma_f32 v[178:179], v[68:69], v[178:179], v[180:181]
	v_max_i32_e32 v180, 0, v194
	v_max_i32_e32 v181, 0, v195
	v_pk_mul_f32 v[182:183], v[70:71], v[182:183]
	v_max_i32_e32 v184, 0, v200
	v_max_i32_e32 v185, 0, v201
	v_pk_add_f32 v[176:177], v[176:177], v[176:177] op_sel:[0,1] op_sel_hi:[1,0]
	v_pk_add_f32 v[178:179], v[178:179], v[178:179] op_sel:[0,1] op_sel_hi:[1,0]
	v_pk_fma_f32 v[180:181], v[68:69], v[180:181], v[182:183]
	v_max_i32_e32 v182, 0, v198
	v_max_i32_e32 v183, 0, v199
	v_pk_mul_f32 v[184:185], v[70:71], v[184:185]
	v_permlane16_swap_b32_e32 v176, v178
	v_pk_fma_f32 v[182:183], v[68:69], v[182:183], v[184:185]
	v_pk_add_f32 v[180:181], v[180:181], v[180:181] op_sel:[0,1] op_sel_hi:[1,0]
	v_pk_add_f32 v[182:183], v[182:183], v[182:183] op_sel:[0,1] op_sel_hi:[1,0]
	v_add_f32_e32 v167, v176, v178
	v_mfma_f32_16x16x32_bf16 v[176:179], v[72:75], v[132:135], 0
	v_permlane16_swap_b32_e32 v180, v182
	v_add_f32_e32 v168, v180, v182
	v_mfma_f32_16x16x32_bf16 v[180:183], v[72:75], v[140:143], 0
	s_nop 0
	v_permlane32_swap_b32_e32 v167, v168
	v_add_f32_e32 v167, v167, v168
	v_mfma_f32_16x16x32_bf16 v[194:197], v[72:75], v[148:151], 0
	v_ashrrev_i32_e32 v168, 31, v167
	v_bitop3_b32 v167, v168, v167, s33 bitop3:0x36
	v_cndmask_b32_e32 v167, 0, v167, vcc
	v_mfma_f32_16x16x32_bf16 v[198:201], v[72:75], v[156:159], 0
	ds_write2st64_b32 v160, v166, v167 offset0:8 offset1:72
	v_cmp_ge_i32_e32 vcc, s13, v175
	v_mfma_f32_16x16x32_bf16 v[176:179], v[76:79], v[128:131], v[176:179]
	v_mfma_f32_16x16x32_bf16 v[180:183], v[76:79], v[136:139], v[180:183]
	v_mfma_f32_16x16x32_bf16 v[194:197], v[76:79], v[144:147], v[194:197]
	s_nop 5
	v_max_i32_e32 v178, 0, v178
	v_max_i32_e32 v179, 0, v179
	v_max_i32_e32 v176, 0, v176
	v_mfma_f32_16x16x32_bf16 v[198:201], v[76:79], v[152:155], v[198:201]
	v_max_i32_e32 v177, 0, v177
	v_pk_mul_f32 v[178:179], v[82:83], v[178:179]
	s_nop 0
	v_pk_fma_f32 v[176:177], v[80:81], v[176:177], v[178:179]
	v_max_i32_e32 v178, 0, v180
	v_max_i32_e32 v179, 0, v181
	v_max_i32_e32 v180, 0, v182
	v_max_i32_e32 v181, 0, v183
	v_pk_mul_f32 v[180:181], v[82:83], v[180:181]
	v_max_i32_e32 v182, 0, v196
	v_max_i32_e32 v183, 0, v197
	v_pk_fma_f32 v[178:179], v[80:81], v[178:179], v[180:181]
	v_max_i32_e32 v180, 0, v194
	v_max_i32_e32 v181, 0, v195
	v_pk_mul_f32 v[182:183], v[82:83], v[182:183]
	v_max_i32_e32 v184, 0, v200
	v_max_i32_e32 v185, 0, v201
	v_pk_add_f32 v[176:177], v[176:177], v[176:177] op_sel:[0,1] op_sel_hi:[1,0]
	v_pk_add_f32 v[178:179], v[178:179], v[178:179] op_sel:[0,1] op_sel_hi:[1,0]
	v_pk_fma_f32 v[180:181], v[80:81], v[180:181], v[182:183]
	v_max_i32_e32 v182, 0, v198
	v_max_i32_e32 v183, 0, v199
	v_pk_mul_f32 v[184:185], v[82:83], v[184:185]
	v_permlane16_swap_b32_e32 v176, v178
	v_pk_fma_f32 v[182:183], v[80:81], v[182:183], v[184:185]
	v_pk_add_f32 v[180:181], v[180:181], v[180:181] op_sel:[0,1] op_sel_hi:[1,0]
	v_pk_add_f32 v[182:183], v[182:183], v[182:183] op_sel:[0,1] op_sel_hi:[1,0]
	v_add_f32_e32 v166, v176, v178
	v_mfma_f32_16x16x32_bf16 v[176:179], v[84:87], v[132:135], 0
	v_permlane16_swap_b32_e32 v180, v182
	v_add_f32_e32 v167, v180, v182
	v_mfma_f32_16x16x32_bf16 v[180:183], v[84:87], v[140:143], 0
	s_nop 0
	v_permlane32_swap_b32_e32 v166, v167
	v_add_f32_e32 v166, v166, v167
	v_mfma_f32_16x16x32_bf16 v[194:197], v[84:87], v[148:151], 0
	v_ashrrev_i32_e32 v167, 31, v166
	v_bitop3_b32 v166, v167, v166, s33 bitop3:0x36
	v_cndmask_b32_e32 v166, 0, v166, vcc
	v_mfma_f32_16x16x32_bf16 v[198:201], v[84:87], v[156:159], 0
	v_cmp_ge_i32_e32 vcc, s14, v175
	v_mfma_f32_16x16x32_bf16 v[176:179], v[88:91], v[128:131], v[176:179]
	v_mfma_f32_16x16x32_bf16 v[180:183], v[88:91], v[136:139], v[180:183]
	v_mfma_f32_16x16x32_bf16 v[194:197], v[88:91], v[144:147], v[194:197]
	s_nop 5
	v_max_i32_e32 v178, 0, v178
	v_max_i32_e32 v179, 0, v179
	v_max_i32_e32 v176, 0, v176
	v_mfma_f32_16x16x32_bf16 v[198:201], v[88:91], v[152:155], v[198:201]
	v_max_i32_e32 v177, 0, v177
	v_pk_mul_f32 v[178:179], v[94:95], v[178:179]
	s_nop 0
	v_pk_fma_f32 v[176:177], v[92:93], v[176:177], v[178:179]
	v_max_i32_e32 v178, 0, v180
	v_max_i32_e32 v179, 0, v181
	v_max_i32_e32 v180, 0, v182
	v_max_i32_e32 v181, 0, v183
	v_pk_mul_f32 v[180:181], v[94:95], v[180:181]
	v_max_i32_e32 v182, 0, v196
	v_max_i32_e32 v183, 0, v197
	v_pk_fma_f32 v[178:179], v[92:93], v[178:179], v[180:181]
	v_max_i32_e32 v180, 0, v194
	v_max_i32_e32 v181, 0, v195
	v_pk_mul_f32 v[182:183], v[94:95], v[182:183]
	v_max_i32_e32 v184, 0, v200
	v_max_i32_e32 v185, 0, v201
	v_pk_fma_f32 v[180:181], v[92:93], v[180:181], v[182:183]
	v_max_i32_e32 v182, 0, v198
	v_max_i32_e32 v183, 0, v199
	v_pk_mul_f32 v[184:185], v[94:95], v[184:185]
	v_pk_add_f32 v[176:177], v[176:177], v[176:177] op_sel:[0,1] op_sel_hi:[1,0]
	v_pk_fma_f32 v[182:183], v[92:93], v[182:183], v[184:185]
	v_pk_add_f32 v[178:179], v[178:179], v[178:179] op_sel:[0,1] op_sel_hi:[1,0]
	v_pk_add_f32 v[180:181], v[180:181], v[180:181] op_sel:[0,1] op_sel_hi:[1,0]
	v_pk_add_f32 v[182:183], v[182:183], v[182:183] op_sel:[0,1] op_sel_hi:[1,0]
	v_permlane16_swap_b32_e32 v176, v178
	s_nop 0
	v_permlane16_swap_b32_e32 v180, v182
	v_add_f32_e32 v167, v176, v178
	v_add_f32_e32 v168, v180, v182
	s_nop 1
	v_permlane32_swap_b32_e32 v167, v168
	v_add_f32_e32 v167, v167, v168
	v_ashrrev_i32_e32 v168, 31, v167
	v_bitop3_b32 v167, v168, v167, s33 bitop3:0x36
	v_cndmask_b32_e32 v167, 0, v167, vcc
	ds_write2st64_b32 v160, v166, v167 offset0:136 offset1:200

; #define IDX_LOADG(dst, grp_) do { _Pragma("unroll") for (int tt = 0; tt < 4; ++tt) { const bf16_t* p_ = ikl + (size_t)(64 * (grp_) + 16 * tt) * 64; dst[tt][0] = *(const bf16x8*)p_; dst[tt][1] = *(const bf16x8*)(p_ + 32); } } while (0)
; DI void idx_rows(LAS unsigned char* lds, int b, int tg, const bf16_t* IQ, const bf16_t* IK, const float* IW, unsigned long long* maskT) {
;     ...
;         __syncthreads();
;         if (wave < ngrp) IDX_LOADG(bA, wave);
;         for (int grp = wave; grp < ngrp; grp += 16) {
;             if (grp + 8 < ngrp) IDX_LOADG(bB, grp + 8);
;             IDX_COMPUTE(bA, grp);
;             if (grp + 8 < ngrp) {
;                 if (grp + 16 < ngrp) IDX_LOADG(bA, grp + 16);
.LBB0_623:
	s_add_i32 s7, s15, 8
	s_cmp_le_i32 s7, s0
	s_cselect_b64 s[8:9], -1, 0
	s_cmp_gt_i32 s7, s0
	s_cbranch_scc1 .LBB0_625
	s_add_i32 s16, s6, 0xfffffdd0
	s_ashr_i32 s17, s16, 31
	s_lshl_b64 s[16:17], s[16:17], 7
	v_lshl_add_u64 v[128:129], v[172:173], 0, s[16:17]
	s_add_i32 s16, s6, 0xfffffde0
	s_ashr_i32 s17, s16, 31
	s_lshl_b64 s[16:17], s[16:17], 7
	v_lshl_add_u64 v[136:137], v[172:173], 0, s[16:17]
	s_add_i32 s16, s6, 0xfffffdf0
	s_ashr_i32 s17, s16, 31
	s_lshl_b64 s[16:17], s[16:17], 7
	v_lshl_add_u64 v[144:145], v[172:173], 0, s[16:17]
	s_add_i32 s16, s6, 0xfffffe00
	s_ashr_i32 s17, s16, 31
	s_lshl_b64 s[16:17], s[16:17], 7
	v_lshl_add_u64 v[152:153], v[172:173], 0, s[16:17]
	global_load_dwordx4 v[132:135], v[128:129], off
	s_nop 0
	global_load_dwordx4 v[128:131], v[128:129], off offset:64
	s_nop 0
	global_load_dwordx4 v[140:143], v[136:137], off
	s_nop 0
	global_load_dwordx4 v[136:139], v[136:137], off offset:64
	s_nop 0
	global_load_dwordx4 v[148:151], v[144:145], off
	s_nop 0
	global_load_dwordx4 v[144:147], v[144:145], off offset:64
	s_nop 0
	global_load_dwordx4 v[156:159], v[152:153], off
	s_nop 0
	global_load_dwordx4 v[152:155], v[152:153], off offset:64
	s_waitcnt vmcnt(8)
	s_branch .Lidx_c1

; #define IDX_LOADG(dst, grp_) do { _Pragma("unroll") for (int tt = 0; tt < 4; ++tt) { const bf16_t* p_ = ikl + (size_t)(64 * (grp_) + 16 * tt) * 64; dst[tt][0] = *(const bf16x8*)p_; dst[tt][1] = *(const bf16x8*)(p_ + 32); } } while (0)
; DI void idx_rows(LAS unsigned char* lds, int b, int tg, const bf16_t* IQ, const bf16_t* IK, const float* IW, unsigned long long* maskT) {
;     ...
;         __syncthreads();
;         if (wave < ngrp) IDX_LOADG(bA, wave);
;         for (int grp = wave; grp < ngrp; grp += 16) {
;             if (grp + 8 < ngrp) IDX_LOADG(bB, grp + 8);
;             IDX_COMPUTE(bA, grp);
.Lidx_c1:
	v_mfma_f32_16x16x32_bf16 v[178:181], v[0:3], v[96:99], 0
	v_add_u32_e32 v175, s6, v174
	v_add_u32_e32 v176, 0xfffffbd0, v175
	v_cmp_ge_i32_e32 vcc, s1, v176
	v_mfma_f32_16x16x32_bf16 v[182:185], v[0:3], v[104:107], 0
	v_add_u32_e32 v166, 0xffff0000, v160
	s_add_i32 s15, s15, 16
	v_mfma_f32_16x16x32_bf16 v[194:197], v[0:3], v[112:115], 0
	v_mfma_f32_16x16x32_bf16 v[198:201], v[0:3], v[120:123], 0
	v_mfma_f32_16x16x32_bf16 v[178:181], v[4:7], v[100:103], v[178:181]
	v_mfma_f32_16x16x32_bf16 v[182:185], v[4:7], v[108:111], v[182:185]
	v_mfma_f32_16x16x32_bf16 v[194:197], v[4:7], v[116:119], v[194:197]
	s_nop 5
	v_max_i32_e32 v180, 0, v180
	v_max_i32_e32 v181, 0, v181
	v_max_i32_e32 v178, 0, v178
	v_mfma_f32_16x16x32_bf16 v[198:201], v[4:7], v[124:127], v[198:201]
	v_max_i32_e32 v179, 0, v179
	v_pk_mul_f32 v[180:181], v[10:11], v[180:181]
	s_nop 0
	v_pk_fma_f32 v[178:179], v[8:9], v[178:179], v[180:181]
	v_max_i32_e32 v180, 0, v182
	v_max_i32_e32 v181, 0, v183
	v_max_i32_e32 v182, 0, v184
	v_max_i32_e32 v183, 0, v185
	v_pk_mul_f32 v[182:183], v[10:11], v[182:183]
	v_max_i32_e32 v184, 0, v196
	v_max_i32_e32 v185, 0, v197
	v_pk_fma_f32 v[180:181], v[8:9], v[180:181], v[182:183]
	v_max_i32_e32 v182, 0, v194
	v_max_i32_e32 v183, 0, v195
	v_pk_mul_f32 v[184:185], v[10:11], v[184:185]
	v_max_i32_e32 v194, 0, v200
	v_max_i32_e32 v195, 0, v201
	v_pk_add_f32 v[178:179], v[178:179], v[178:179] op_sel:[0,1] op_sel_hi:[1,0]
	v_pk_add_f32 v[180:181], v[180:181], v[180:181] op_sel:[0,1] op_sel_hi:[1,0]
	v_pk_fma_f32 v[182:183], v[8:9], v[182:183], v[184:185]
	v_max_i32_e32 v184, 0, v198
	v_max_i32_e32 v185, 0, v199
	v_pk_mul_f32 v[194:195], v[10:11], v[194:195]
	v_permlane16_swap_b32_e32 v178, v180
	v_pk_fma_f32 v[184:185], v[8:9], v[184:185], v[194:195]
	v_pk_add_f32 v[182:183], v[182:183], v[182:183] op_sel:[0,1] op_sel_hi:[1,0]
	v_pk_add_f32 v[184:185], v[184:185], v[184:185] op_sel:[0,1] op_sel_hi:[1,0]
	v_add_f32_e32 v167, v178, v180
	v_mfma_f32_16x16x32_bf16 v[178:181], v[12:15], v[96:99], 0
	v_permlane16_swap_b32_e32 v182, v184
	v_add_f32_e32 v168, v182, v184
	v_mfma_f32_16x16x32_bf16 v[182:185], v[12:15], v[104:107], 0
	s_nop 0
	v_permlane32_swap_b32_e32 v167, v168
	v_add_f32_e32 v167, v167, v168
	v_mfma_f32_16x16x32_bf16 v[194:197], v[12:15], v[112:115], 0
	v_ashrrev_i32_e32 v168, 31, v167
	v_bitop3_b32 v167, v168, v167, s33 bitop3:0x36
	v_cndmask_b32_e32 v167, 0, v167, vcc
	v_mfma_f32_16x16x32_bf16 v[198:201], v[12:15], v[120:123], 0
	ds_write_b32 v166, v167
	v_cmp_ge_i32_e32 vcc, s4, v176
	v_mfma_f32_16x16x32_bf16 v[178:181], v[16:19], v[100:103], v[178:181]
	v_mfma_f32_16x16x32_bf16 v[182:185], v[16:19], v[108:111], v[182:185]
	v_mfma_f32_16x16x32_bf16 v[194:197], v[16:19], v[116:119], v[194:197]
	s_nop 5
	v_max_i32_e32 v180, 0, v180
	v_max_i32_e32 v181, 0, v181
	v_max_i32_e32 v178, 0, v178
	v_mfma_f32_16x16x32_bf16 v[198:201], v[16:19], v[124:127], v[198:201]
	v_max_i32_e32 v179, 0, v179
	v_pk_mul_f32 v[180:181], v[22:23], v[180:181]
	s_nop 0
	v_pk_fma_f32 v[178:179], v[20:21], v[178:179], v[180:181]
	v_max_i32_e32 v180, 0, v182
	v_max_i32_e32 v181, 0, v183
	v_max_i32_e32 v182, 0, v184
	v_max_i32_e32 v183, 0, v185
	v_pk_mul_f32 v[182:183], v[22:23], v[182:183]
	v_max_i32_e32 v184, 0, v196
	v_max_i32_e32 v185, 0, v197
	v_pk_fma_f32 v[180:181], v[20:21], v[180:181], v[182:183]
	v_max_i32_e32 v182, 0, v194
	v_max_i32_e32 v183, 0, v195
	v_pk_mul_f32 v[184:185], v[22:23], v[184:185]
	v_max_i32_e32 v194, 0, v200
	v_max_i32_e32 v195, 0, v201
	v_pk_add_f32 v[178:179], v[178:179], v[178:179] op_sel:[0,1] op_sel_hi:[1,0]
	v_pk_add_f32 v[180:181], v[180:181], v[180:181] op_sel:[0,1] op_sel_hi:[1,0]
	v_pk_fma_f32 v[182:183], v[20:21], v[182:183], v[184:185]
	v_max_i32_e32 v184, 0, v198
	v_max_i32_e32 v185, 0, v199
	v_pk_mul_f32 v[194:195], v[22:23], v[194:195]
	v_permlane16_swap_b32_e32 v178, v180
	v_pk_fma_f32 v[184:185], v[20:21], v[184:185], v[194:195]
	v_pk_add_f32 v[182:183], v[182:183], v[182:183] op_sel:[0,1] op_sel_hi:[1,0]
	v_pk_add_f32 v[184:185], v[184:185], v[184:185] op_sel:[0,1] op_sel_hi:[1,0]
	v_add_f32_e32 v166, v178, v180
	v_mfma_f32_16x16x32_bf16 v[178:181], v[24:27], v[96:99], 0
	v_permlane16_swap_b32_e32 v182, v184
	v_add_f32_e32 v167, v182, v184
	v_mfma_f32_16x16x32_bf16 v[182:185], v[24:27], v[104:107], 0
	s_nop 0
	v_permlane32_swap_b32_e32 v166, v167
	v_add_f32_e32 v166, v166, v167
	v_mfma_f32_16x16x32_bf16 v[194:197], v[24:27], v[112:115], 0
	v_ashrrev_i32_e32 v167, 31, v166
	v_bitop3_b32 v166, v167, v166, s33 bitop3:0x36
	v_cndmask_b32_e32 v166, 0, v166, vcc
	v_mfma_f32_16x16x32_bf16 v[198:201], v[24:27], v[120:123], 0
	v_add_u32_e32 v167, 0xffff4000, v160
	ds_write_b32 v167, v166
	v_cmp_ge_i32_e32 vcc, s5, v176
	v_mfma_f32_16x16x32_bf16 v[178:181], v[28:31], v[100:103], v[178:181]
	v_mfma_f32_16x16x32_bf16 v[182:185], v[28:31], v[108:111], v[182:185]
	v_mfma_f32_16x16x32_bf16 v[194:197], v[28:31], v[116:119], v[194:197]
	s_nop 5
	v_max_i32_e32 v180, 0, v180
	v_max_i32_e32 v181, 0, v181
	v_max_i32_e32 v178, 0, v178
	v_mfma_f32_16x16x32_bf16 v[198:201], v[28:31], v[124:127], v[198:201]
	v_max_i32_e32 v179, 0, v179
	v_pk_mul_f32 v[180:181], v[34:35], v[180:181]
	s_nop 0
	v_pk_fma_f32 v[178:179], v[32:33], v[178:179], v[180:181]
	v_max_i32_e32 v180, 0, v182
	v_max_i32_e32 v181, 0, v183
	v_max_i32_e32 v182, 0, v184
	v_max_i32_e32 v183, 0, v185
	v_pk_mul_f32 v[182:183], v[34:35], v[182:183]
	v_max_i32_e32 v184, 0, v196
	v_max_i32_e32 v185, 0, v197
	v_pk_fma_f32 v[180:181], v[32:33], v[180:181], v[182:183]
	v_max_i32_e32 v182, 0, v194
	v_max_i32_e32 v183, 0, v195
	v_pk_mul_f32 v[184:185], v[34:35], v[184:185]
	v_max_i32_e32 v194, 0, v200
	v_max_i32_e32 v195, 0, v201
	v_pk_add_f32 v[178:179], v[178:179], v[178:179] op_sel:[0,1] op_sel_hi:[1,0]
	v_pk_add_f32 v[180:181], v[180:181], v[180:181] op_sel:[0,1] op_sel_hi:[1,0]
	v_pk_fma_f32 v[182:183], v[32:33], v[182:183], v[184:185]
	v_max_i32_e32 v184, 0, v198
	v_max_i32_e32 v185, 0, v199
	v_pk_mul_f32 v[194:195], v[34:35], v[194:195]
	v_permlane16_swap_b32_e32 v178, v180
	v_pk_fma_f32 v[184:185], v[32:33], v[184:185], v[194:195]
	v_pk_add_f32 v[182:183], v[182:183], v[182:183] op_sel:[0,1] op_sel_hi:[1,0]
	v_pk_add_f32 v[184:185], v[184:185], v[184:185] op_sel:[0,1] op_sel_hi:[1,0]
	v_add_f32_e32 v166, v178, v180
	v_mfma_f32_16x16x32_bf16 v[178:181], v[36:39], v[96:99], 0
	v_permlane16_swap_b32_e32 v182, v184
	v_add_f32_e32 v167, v182, v184
	v_mfma_f32_16x16x32_bf16 v[182:185], v[36:39], v[104:107], 0
	s_nop 0
	v_permlane32_swap_b32_e32 v166, v167
	v_add_f32_e32 v166, v166, v167
	v_mfma_f32_16x16x32_bf16 v[194:197], v[36:39], v[112:115], 0
	v_ashrrev_i32_e32 v167, 31, v166
	v_bitop3_b32 v166, v167, v166, s33 bitop3:0x36
	v_cndmask_b32_e32 v166, 0, v166, vcc
	v_mfma_f32_16x16x32_bf16 v[198:201], v[36:39], v[120:123], 0
	v_add_u32_e32 v167, 0xffff8000, v160
	ds_write_b32 v167, v166
	v_cmp_ge_i32_e32 vcc, s10, v176
	v_mfma_f32_16x16x32_bf16 v[178:181], v[40:43], v[100:103], v[178:181]
	v_mfma_f32_16x16x32_bf16 v[182:185], v[40:43], v[108:111], v[182:185]
	v_mfma_f32_16x16x32_bf16 v[194:197], v[40:43], v[116:119], v[194:197]
	s_nop 5
	v_max_i32_e32 v180, 0, v180
	v_max_i32_e32 v181, 0, v181
	v_max_i32_e32 v178, 0, v178
	v_mfma_f32_16x16x32_bf16 v[198:201], v[40:43], v[124:127], v[198:201]
	v_max_i32_e32 v179, 0, v179
	v_pk_mul_f32 v[180:181], v[46:47], v[180:181]
	s_nop 0
	v_pk_fma_f32 v[178:179], v[44:45], v[178:179], v[180:181]
	v_max_i32_e32 v180, 0, v182
	v_max_i32_e32 v181, 0, v183
	v_max_i32_e32 v182, 0, v184
	v_max_i32_e32 v183, 0, v185
	v_pk_mul_f32 v[182:183], v[46:47], v[182:183]
	v_max_i32_e32 v184, 0, v196
	v_max_i32_e32 v185, 0, v197
	v_pk_fma_f32 v[180:181], v[44:45], v[180:181], v[182:183]
	v_max_i32_e32 v182, 0, v194
	v_max_i32_e32 v183, 0, v195
	v_pk_mul_f32 v[184:185], v[46:47], v[184:185]
	v_max_i32_e32 v194, 0, v200
	v_max_i32_e32 v195, 0, v201
	v_pk_add_f32 v[178:179], v[178:179], v[178:179] op_sel:[0,1] op_sel_hi:[1,0]
	v_pk_add_f32 v[180:181], v[180:181], v[180:181] op_sel:[0,1] op_sel_hi:[1,0]
	v_pk_fma_f32 v[182:183], v[44:45], v[182:183], v[184:185]
	v_max_i32_e32 v184, 0, v198
	v_max_i32_e32 v185, 0, v199
	v_pk_mul_f32 v[194:195], v[46:47], v[194:195]
	v_permlane16_swap_b32_e32 v178, v180
	v_pk_fma_f32 v[184:185], v[44:45], v[184:185], v[194:195]
	v_pk_add_f32 v[182:183], v[182:183], v[182:183] op_sel:[0,1] op_sel_hi:[1,0]
	v_pk_add_f32 v[184:185], v[184:185], v[184:185] op_sel:[0,1] op_sel_hi:[1,0]
	v_add_f32_e32 v166, v178, v180
	v_mfma_f32_16x16x32_bf16 v[178:181], v[48:51], v[96:99], 0
	v_permlane16_swap_b32_e32 v182, v184
	v_add_f32_e32 v167, v182, v184
	v_mfma_f32_16x16x32_bf16 v[182:185], v[48:51], v[104:107], 0
	s_nop 0
	v_permlane32_swap_b32_e32 v166, v167
	v_add_f32_e32 v166, v166, v167
	v_mfma_f32_16x16x32_bf16 v[194:197], v[48:51], v[112:115], 0
	v_ashrrev_i32_e32 v167, 31, v166
	v_bitop3_b32 v166, v167, v166, s33 bitop3:0x36
	v_cndmask_b32_e32 v166, 0, v166, vcc
	v_mfma_f32_16x16x32_bf16 v[198:201], v[48:51], v[120:123], 0
	v_add_u32_e32 v167, 0xffffc000, v160
	ds_write_b32 v167, v166
	v_cmp_ge_i32_e32 vcc, s11, v176
	v_mfma_f32_16x16x32_bf16 v[178:181], v[52:55], v[100:103], v[178:181]
	v_mfma_f32_16x16x32_bf16 v[182:185], v[52:55], v[108:111], v[182:185]
	v_mfma_f32_16x16x32_bf16 v[194:197], v[52:55], v[116:119], v[194:197]
	s_nop 5
	v_max_i32_e32 v180, 0, v180
	v_max_i32_e32 v181, 0, v181
	v_max_i32_e32 v178, 0, v178
	v_mfma_f32_16x16x32_bf16 v[198:201], v[52:55], v[124:127], v[198:201]
	v_max_i32_e32 v179, 0, v179
	v_pk_mul_f32 v[180:181], v[58:59], v[180:181]
	s_nop 0
	v_pk_fma_f32 v[178:179], v[56:57], v[178:179], v[180:181]
	v_max_i32_e32 v180, 0, v182
	v_max_i32_e32 v181, 0, v183
	v_max_i32_e32 v182, 0, v184
	v_max_i32_e32 v183, 0, v185
	v_pk_mul_f32 v[182:183], v[58:59], v[182:183]
	v_max_i32_e32 v184, 0, v196
	v_max_i32_e32 v185, 0, v197
	v_pk_fma_f32 v[180:181], v[56:57], v[180:181], v[182:183]
	v_max_i32_e32 v182, 0, v194
	v_max_i32_e32 v183, 0, v195
	v_pk_mul_f32 v[184:185], v[58:59], v[184:185]
	v_max_i32_e32 v194, 0, v200
	v_max_i32_e32 v195, 0, v201
	v_pk_add_f32 v[178:179], v[178:179], v[178:179] op_sel:[0,1] op_sel_hi:[1,0]
	v_pk_add_f32 v[180:181], v[180:181], v[180:181] op_sel:[0,1] op_sel_hi:[1,0]
	v_pk_fma_f32 v[182:183], v[56:57], v[182:183], v[184:185]
	v_max_i32_e32 v184, 0, v198
	v_max_i32_e32 v185, 0, v199
	v_pk_mul_f32 v[194:195], v[58:59], v[194:195]
	v_permlane16_swap_b32_e32 v178, v180
	v_pk_fma_f32 v[184:185], v[56:57], v[184:185], v[194:195]
	v_pk_add_f32 v[182:183], v[182:183], v[182:183] op_sel:[0,1] op_sel_hi:[1,0]
	v_pk_add_f32 v[184:185], v[184:185], v[184:185] op_sel:[0,1] op_sel_hi:[1,0]
	v_add_f32_e32 v166, v178, v180
	v_mfma_f32_16x16x32_bf16 v[178:181], v[60:63], v[96:99], 0
	v_permlane16_swap_b32_e32 v182, v184
	v_add_f32_e32 v167, v182, v184
	v_mfma_f32_16x16x32_bf16 v[182:185], v[60:63], v[104:107], 0
	s_nop 0
	v_permlane32_swap_b32_e32 v166, v167
	v_add_f32_e32 v166, v166, v167
	v_mfma_f32_16x16x32_bf16 v[194:197], v[60:63], v[112:115], 0
	v_ashrrev_i32_e32 v167, 31, v166
	v_bitop3_b32 v166, v167, v166, s33 bitop3:0x36
	v_cndmask_b32_e32 v166, 0, v166, vcc
	v_mfma_f32_16x16x32_bf16 v[198:201], v[60:63], v[120:123], 0
	v_cmp_ge_i32_e32 vcc, s12, v176
	v_mfma_f32_16x16x32_bf16 v[178:181], v[64:67], v[100:103], v[178:181]
; #define IDX_LOADG(dst, grp_) do { _Pragma("unroll") for (int tt = 0; tt < 4; ++tt) { const bf16_t* p_ = ikl + (size_t)(64 * (grp_) + 16 * tt) * 64; dst[tt][0] = *(const bf16x8*)p_; dst[tt][1] = *(const bf16x8*)(p_ + 32); } } while (0)
; DI void idx_rows(LAS unsigned char* lds, int b, int tg, const bf16_t* IQ, const bf16_t* IK, const float* IW, unsigned long long* maskT) {
;     ...
;         __syncthreads();
;         if (wave < ngrp) IDX_LOADG(bA, wave);
;         for (int grp = wave; grp < ngrp; grp += 16) {
;             if (grp + 8 < ngrp) IDX_LOADG(bB, grp + 8);
;             IDX_COMPUTE(bA, grp);
;             if (grp + 8 < ngrp) {
;                 if (grp + 16 < ngrp) IDX_LOADG(bA, grp + 16);
;                 IDX_COMPUTE(bB, grp + 8);
	v_mfma_f32_16x16x32_bf16 v[182:185], v[64:67], v[108:111], v[182:185]
	v_mfma_f32_16x16x32_bf16 v[194:197], v[64:67], v[116:119], v[194:197]
	s_nop 5
	v_max_i32_e32 v180, 0, v180
	v_max_i32_e32 v181, 0, v181
	v_max_i32_e32 v178, 0, v178
	v_mfma_f32_16x16x32_bf16 v[198:201], v[64:67], v[124:127], v[198:201]
	v_max_i32_e32 v179, 0, v179
	v_pk_mul_f32 v[180:181], v[70:71], v[180:181]
	s_nop 0
	v_pk_fma_f32 v[178:179], v[68:69], v[178:179], v[180:181]
	v_max_i32_e32 v180, 0, v182
	v_max_i32_e32 v181, 0, v183
	v_max_i32_e32 v182, 0, v184
	v_max_i32_e32 v183, 0, v185
	v_pk_mul_f32 v[182:183], v[70:71], v[182:183]
	v_max_i32_e32 v184, 0, v196
	v_max_i32_e32 v185, 0, v197
	v_pk_fma_f32 v[180:181], v[68:69], v[180:181], v[182:183]
	v_max_i32_e32 v182, 0, v194
	v_max_i32_e32 v183, 0, v195
	v_pk_mul_f32 v[184:185], v[70:71], v[184:185]
	v_max_i32_e32 v194, 0, v200
	v_max_i32_e32 v195, 0, v201
	v_pk_add_f32 v[178:179], v[178:179], v[178:179] op_sel:[0,1] op_sel_hi:[1,0]
	v_pk_add_f32 v[180:181], v[180:181], v[180:181] op_sel:[0,1] op_sel_hi:[1,0]
	v_pk_fma_f32 v[182:183], v[68:69], v[182:183], v[184:185]
	v_max_i32_e32 v184, 0, v198
	v_max_i32_e32 v185, 0, v199
	v_pk_mul_f32 v[194:195], v[70:71], v[194:195]
	v_permlane16_swap_b32_e32 v178, v180
	v_pk_fma_f32 v[184:185], v[68:69], v[184:185], v[194:195]
	v_pk_add_f32 v[182:183], v[182:183], v[182:183] op_sel:[0,1] op_sel_hi:[1,0]
	v_pk_add_f32 v[184:185], v[184:185], v[184:185] op_sel:[0,1] op_sel_hi:[1,0]
	v_add_f32_e32 v167, v178, v180
	v_mfma_f32_16x16x32_bf16 v[178:181], v[72:75], v[96:99], 0
	v_permlane16_swap_b32_e32 v182, v184
	v_add_f32_e32 v168, v182, v184
	v_mfma_f32_16x16x32_bf16 v[182:185], v[72:75], v[104:107], 0
	s_nop 0
	v_permlane32_swap_b32_e32 v167, v168
	v_add_f32_e32 v167, v167, v168
	v_mfma_f32_16x16x32_bf16 v[194:197], v[72:75], v[112:115], 0
	v_ashrrev_i32_e32 v168, 31, v167
	v_bitop3_b32 v167, v168, v167, s33 bitop3:0x36
	v_cndmask_b32_e32 v167, 0, v167, vcc
	v_mfma_f32_16x16x32_bf16 v[198:201], v[72:75], v[120:123], 0
	ds_write2st64_b32 v160, v166, v167 offset1:64
	v_cmp_ge_i32_e32 vcc, s13, v176
	v_mfma_f32_16x16x32_bf16 v[178:181], v[76:79], v[100:103], v[178:181]
	v_mfma_f32_16x16x32_bf16 v[182:185], v[76:79], v[108:111], v[182:185]
	v_mfma_f32_16x16x32_bf16 v[194:197], v[76:79], v[116:119], v[194:197]
	s_nop 5
	v_max_i32_e32 v180, 0, v180
	v_max_i32_e32 v181, 0, v181
	v_max_i32_e32 v178, 0, v178
	v_mfma_f32_16x16x32_bf16 v[198:201], v[76:79], v[124:127], v[198:201]
	v_max_i32_e32 v179, 0, v179
	v_pk_mul_f32 v[180:181], v[82:83], v[180:181]
	s_nop 0
	v_pk_fma_f32 v[178:179], v[80:81], v[178:179], v[180:181]
	v_max_i32_e32 v180, 0, v182
	v_max_i32_e32 v181, 0, v183
	v_max_i32_e32 v182, 0, v184
	v_max_i32_e32 v183, 0, v185
	v_pk_mul_f32 v[182:183], v[82:83], v[182:183]
	v_max_i32_e32 v184, 0, v196
	v_max_i32_e32 v185, 0, v197
	v_pk_fma_f32 v[180:181], v[80:81], v[180:181], v[182:183]
	v_max_i32_e32 v182, 0, v194
	v_max_i32_e32 v183, 0, v195
	v_pk_mul_f32 v[184:185], v[82:83], v[184:185]
	v_max_i32_e32 v194, 0, v200
	v_max_i32_e32 v195, 0, v201
	v_pk_add_f32 v[178:179], v[178:179], v[178:179] op_sel:[0,1] op_sel_hi:[1,0]
	v_pk_add_f32 v[180:181], v[180:181], v[180:181] op_sel:[0,1] op_sel_hi:[1,0]
	v_pk_fma_f32 v[182:183], v[80:81], v[182:183], v[184:185]
	v_max_i32_e32 v184, 0, v198
	v_max_i32_e32 v185, 0, v199
	v_pk_mul_f32 v[194:195], v[82:83], v[194:195]
	v_permlane16_swap_b32_e32 v178, v180
	v_pk_fma_f32 v[184:185], v[80:81], v[184:185], v[194:195]
	v_pk_add_f32 v[182:183], v[182:183], v[182:183] op_sel:[0,1] op_sel_hi:[1,0]
	v_pk_add_f32 v[184:185], v[184:185], v[184:185] op_sel:[0,1] op_sel_hi:[1,0]
	v_add_f32_e32 v166, v178, v180
	v_mfma_f32_16x16x32_bf16 v[178:181], v[84:87], v[96:99], 0
	v_permlane16_swap_b32_e32 v182, v184
	v_add_f32_e32 v167, v182, v184
	v_mfma_f32_16x16x32_bf16 v[182:185], v[84:87], v[104:107], 0
	s_nop 0
	v_permlane32_swap_b32_e32 v166, v167
	v_add_f32_e32 v166, v166, v167
	v_mfma_f32_16x16x32_bf16 v[194:197], v[84:87], v[112:115], 0
	v_ashrrev_i32_e32 v167, 31, v166
	v_bitop3_b32 v166, v167, v166, s33 bitop3:0x36
	v_cndmask_b32_e32 v166, 0, v166, vcc
	v_mfma_f32_16x16x32_bf16 v[198:201], v[84:87], v[120:123], 0
	v_cmp_ge_i32_e32 vcc, s14, v176
	v_mfma_f32_16x16x32_bf16 v[178:181], v[88:91], v[100:103], v[178:181]
	v_mfma_f32_16x16x32_bf16 v[182:185], v[88:91], v[108:111], v[182:185]
	v_mfma_f32_16x16x32_bf16 v[194:197], v[88:91], v[116:119], v[194:197]
	s_nop 5
	v_max_i32_e32 v180, 0, v180
	v_max_i32_e32 v181, 0, v181
	v_max_i32_e32 v178, 0, v178
	v_mfma_f32_16x16x32_bf16 v[198:201], v[88:91], v[124:127], v[198:201]
	v_max_i32_e32 v179, 0, v179
	v_pk_mul_f32 v[180:181], v[94:95], v[180:181]
	s_nop 0
	v_pk_fma_f32 v[178:179], v[92:93], v[178:179], v[180:181]
	v_max_i32_e32 v180, 0, v182
	v_max_i32_e32 v181, 0, v183
	v_max_i32_e32 v182, 0, v184
	v_max_i32_e32 v183, 0, v185
	v_pk_mul_f32 v[182:183], v[94:95], v[182:183]
	v_max_i32_e32 v184, 0, v196
	v_max_i32_e32 v185, 0, v197
	v_pk_fma_f32 v[180:181], v[92:93], v[180:181], v[182:183]
	v_max_i32_e32 v182, 0, v194
	v_max_i32_e32 v183, 0, v195
	v_pk_mul_f32 v[184:185], v[94:95], v[184:185]
	v_max_i32_e32 v194, 0, v200
	v_max_i32_e32 v195, 0, v201
	v_pk_fma_f32 v[182:183], v[92:93], v[182:183], v[184:185]
	v_max_i32_e32 v184, 0, v198
	v_max_i32_e32 v185, 0, v199
	v_pk_mul_f32 v[194:195], v[94:95], v[194:195]
	v_pk_add_f32 v[178:179], v[178:179], v[178:179] op_sel:[0,1] op_sel_hi:[1,0]
	v_pk_fma_f32 v[184:185], v[92:93], v[184:185], v[194:195]
	v_pk_add_f32 v[180:181], v[180:181], v[180:181] op_sel:[0,1] op_sel_hi:[1,0]
	v_pk_add_f32 v[182:183], v[182:183], v[182:183] op_sel:[0,1] op_sel_hi:[1,0]
	v_pk_add_f32 v[184:185], v[184:185], v[184:185] op_sel:[0,1] op_sel_hi:[1,0]
	v_permlane16_swap_b32_e32 v178, v180
	s_nop 0
	v_permlane16_swap_b32_e32 v182, v184
	v_add_f32_e32 v167, v178, v180
	v_add_f32_e32 v168, v182, v184
	s_nop 1
	v_permlane32_swap_b32_e32 v167, v168
	v_add_f32_e32 v167, v167, v168
	v_ashrrev_i32_e32 v168, 31, v167
	v_bitop3_b32 v167, v168, v167, s33 bitop3:0x36
	v_cndmask_b32_e32 v167, 0, v167, vcc
	s_andn2_b64 vcc, exec, s[8:9]
	ds_write2st64_b32 v160, v166, v167 offset0:128 offset1:192
	s_cbranch_vccnz .LBB0_622
; #define IDX_LOADG(dst, grp_) do { _Pragma("unroll") for (int tt = 0; tt < 4; ++tt) { const bf16_t* p_ = ikl + (size_t)(64 * (grp_) + 16 * tt) * 64; dst[tt][0] = *(const bf16x8*)p_; dst[tt][1] = *(const bf16x8*)(p_ + 32); } } while (0)
; DI void idx_rows(LAS unsigned char* lds, int b, int tg, const bf16_t* IQ, const bf16_t* IK, const float* IW, unsigned long long* maskT) {
;     ...
;         __syncthreads();
;         if (wave < ngrp) IDX_LOADG(bA, wave);
;         for (int grp = wave; grp < ngrp; grp += 16) {
;             if (grp + 8 < ngrp) IDX_LOADG(bB, grp + 8);
;             IDX_COMPUTE(bA, grp);
;             if (grp + 8 < ngrp) {
;                 if (grp + 16 < ngrp) IDX_LOADG(bA, grp + 16);
;                 IDX_COMPUTE(bB, grp + 8);
;             }
;         }
	s_cmp_gt_i32 s15, s0
	s_cbranch_scc1 .LBB0_621
	s_sub_i32 s8, s6, 48
	s_ashr_i32 s9, s8, 31
	s_lshl_b64 s[8:9], s[8:9], 7
	v_lshl_add_u64 v[100:101], v[172:173], 0, s[8:9]
	s_sub_i32 s8, s6, 32
	s_ashr_i32 s9, s8, 31
	s_lshl_b64 s[8:9], s[8:9], 7
	v_lshl_add_u64 v[108:109], v[172:173], 0, s[8:9]
	s_add_i32 s8, s6, -16
	s_ashr_i32 s9, s8, 31
	s_lshl_b64 s[8:9], s[8:9], 7
	s_ashr_i32 s7, s6, 31
	v_lshl_add_u64 v[116:117], v[172:173], 0, s[8:9]
	s_lshl_b64 s[8:9], s[6:7], 7
	v_lshl_add_u64 v[124:125], v[172:173], 0, s[8:9]
	global_load_dwordx4 v[96:99], v[100:101], off
	s_nop 0
	global_load_dwordx4 v[100:103], v[100:101], off offset:64
	s_nop 0
	global_load_dwordx4 v[104:107], v[108:109], off
	s_nop 0
	global_load_dwordx4 v[108:111], v[108:109], off offset:64
	s_nop 0
	global_load_dwordx4 v[112:115], v[116:117], off
	s_nop 0
	global_load_dwordx4 v[116:119], v[116:117], off offset:64
	s_nop 0
	global_load_dwordx4 v[120:123], v[124:125], off
	s_nop 0
	global_load_dwordx4 v[124:127], v[124:125], off offset:64
	s_waitcnt vmcnt(8)
	s_branch .Lidx_c2

; #define LAS __attribute__((address_space(3)))
; DI int fresh_tid() { int t = threadIdx.x; asm volatile("" : "+v"(t)); return t; }
; template <bool MASK>
; DI void attn_unit(LAS unsigned char* lds, const bf16_t* qrow, const bf16_t* kbase, int kpitch, const bf16_t* vtbase, int vtpitch, int ntiles,
;                   const unsigned long long* maskp, bf16_t* orow, float c1, float c2) {
;     const int tid = fresh_tid(), lane = tid & 63, r = lane & 31, h = lane >> 5;
;     bf16x8 qf[8];
; #pragma unroll
;     for (int ks = 0; ks < 8; ++ks) qf[ks] = *(const bf16x8*)(qrow + 16 * ks + 8 * h);
;     f32x16 o[4];
; #pragma unroll
;     for (int d = 0; d < 4; ++d)
; #pragma unroll
;         for (int i = 0; i < 16; ++i) o[d][i] = 0.f;
;     float l = 0.f;
;     u32x4 pk[2], pv[2];
;     const int ke0 = tid, ke1 = tid + 512;
;     const bf16_t* kg0 = kbase + (size_t)(ke0 >> 4) * kpitch + (ke0 & 15) * 8; const bf16_t* kg1 = kbase + (size_t)(ke1 >> 4) * kpitch + (ke1 & 15) * 8;
;     const int kl0 = (ke0 >> 4) * AK_PITCH + (ke0 & 15) * 16, kl1 = (ke1 >> 4) * AK_PITCH + (ke1 & 15) * 16;
;     const bf16_t* vg0 = vtbase + (size_t)(ke0 >> 3) * vtpitch + (ke0 & 7) * 8; const bf16_t* vg1 = vtbase + (size_t)(ke1 >> 3) * vtpitch + (ke1 & 7) * 8;
;     const int vl0 = AK_BYTES + (ke0 >> 3) * AV_PITCH + (ke0 & 7) * 16, vl1 = AK_BYTES + (ke1 >> 3) * AV_PITCH + (ke1 & 7) * 16;
;     pk[0] = *(const u32x4*)kg0; pk[1] = *(const u32x4*)kg1; pv[0] = *(const u32x4*)vg0; pv[1] = *(const u32x4*)vg1;
;     {
;         LAS unsigned char* nb = lds;
;         *(LAS u32x4*)(nb + kl0) = pk[0]; *(LAS u32x4*)(nb + kl1) = pk[1];
;         *(LAS u32x2*)(nb + vl0) = (u32x2){pv[0].x, pv[0].y}; *(LAS u32x2*)(nb + vl0 + 8) = (u32x2){pv[0].z, pv[0].w};
;         *(LAS u32x2*)(nb + vl1) = (u32x2){pv[1].x, pv[1].y}; *(LAS u32x2*)(nb + vl1 + 8) = (u32x2){pv[1].z, pv[1].w};
;     }
;     unsigned long long mw_next = ~0ull;
;     if (MASK) mw_next = maskp[0];
;     __syncthreads();
.LBB0_1243:
	v_mov_b32_e32 v63, 0
	s_andn2_b64 vcc, exec, s[2:3]
	v_mov_b32_e32 v62, v63
	v_mov_b32_e32 v61, v63
	v_mov_b32_e32 v60, v63
	v_mov_b32_e32 v59, v63
	v_mov_b32_e32 v58, v63
	v_mov_b32_e32 v57, v63
	v_mov_b32_e32 v56, v63
	v_mov_b32_e32 v55, v63
	v_mov_b32_e32 v54, v63
	v_mov_b32_e32 v53, v63
	v_mov_b32_e32 v52, v63
	v_mov_b32_e32 v51, v63
	v_mov_b32_e32 v50, v63
	v_mov_b32_e32 v49, v63
	v_mov_b32_e32 v48, v63
	v_mov_b32_e32 v47, v63
	v_mov_b32_e32 v46, v63
	v_mov_b32_e32 v45, v63
	v_mov_b32_e32 v44, v63
	v_mov_b32_e32 v43, v63
	v_mov_b32_e32 v42, v63
	v_mov_b32_e32 v41, v63
	v_mov_b32_e32 v40, v63
	v_mov_b32_e32 v39, v63
	v_mov_b32_e32 v38, v63
	v_mov_b32_e32 v37, v63
	v_mov_b32_e32 v36, v63
	v_mov_b32_e32 v35, v63
	v_mov_b32_e32 v34, v63
	v_mov_b32_e32 v33, v63
	v_mov_b32_e32 v32, v63
	v_mov_b32_e32 v31, v63
	v_mov_b32_e32 v30, v63
	v_mov_b32_e32 v29, v63
	v_mov_b32_e32 v28, v63
	v_mov_b32_e32 v27, v63
	v_mov_b32_e32 v26, v63
	v_mov_b32_e32 v25, v63
	v_mov_b32_e32 v24, v63
	v_mov_b32_e32 v23, v63
	v_mov_b32_e32 v22, v63
	v_mov_b32_e32 v21, v63
	v_mov_b32_e32 v20, v63
	v_mov_b32_e32 v19, v63
	v_mov_b32_e32 v18, v63
	v_mov_b32_e32 v17, v63
	v_mov_b32_e32 v16, v63
	v_mov_b32_e32 v15, v63
	v_mov_b32_e32 v14, v63
	v_mov_b32_e32 v13, v63
	v_mov_b32_e32 v12, v63
	v_mov_b32_e32 v11, v63
	v_mov_b32_e32 v10, v63
	v_mov_b32_e32 v9, v63
	v_mov_b32_e32 v8, v63
	v_mov_b32_e32 v7, v63
	v_mov_b32_e32 v6, v63
	v_mov_b32_e32 v5, v63
	v_mov_b32_e32 v4, v63
	v_mov_b32_e32 v3, v63
	v_mov_b32_e32 v2, v63
	v_mov_b32_e32 v1, v63
	v_mov_b32_e32 v0, v63
	v_mov_b32_e32 v149, v63
	s_mov_b64 s[30:31], 0x8000
	s_cbranch_vccnz .LBB0_1238
	s_add_i32 s17, s16, 1
	s_add_u32 s2, s18, s22
	s_addc_u32 s3, 0, 0
	s_add_u32 s2, s2, 0x20908000
	v_and_b32_e32 v0, 31, v65
	s_addc_u32 s3, s3, 0
	v_and_b32_e32 v2, 15, v65
	v_mul_u32_u24_e32 v153, 0x110, v0
	v_mul_u32_u24_e32 v180, 0x88, v0
	v_lshl_add_u64 v[0:1], s[2:3], 0, v[68:69]
	v_lshlrev_b32_e32 v2, 4, v2
	v_mov_b32_e32 v3, v161
	v_lshl_add_u64 v[154:155], v[0:1], 0, v[2:3]
	v_lshl_add_u64 v[0:1], s[2:3], 0, v[70:71]
	s_add_u32 s2, s19, 0x21100080
	v_lshl_add_u64 v[156:157], v[0:1], 0, v[2:3]
	s_addc_u32 s3, 0, 0
	v_and_b32_e32 v2, 7, v65
	v_lshl_add_u64 v[0:1], s[2:3], 0, v[72:73]
	v_lshlrev_b32_e32 v2, 4, v2
	v_lshl_add_u64 v[158:159], v[0:1], 0, v[2:3]
	v_lshl_add_u64 v[0:1], s[2:3], 0, v[74:75]
	s_add_u32 s2, s18, 0x23e08000
	s_addc_u32 s3, 0, 0
	v_mov_b32_e32 v149, 0
	v_lshlrev_b32_e32 v151, 3, v76
	v_lshl_add_u64 v[170:171], v[0:1], 0, v[2:3]
	v_lshl_add_u64 v[172:173], v[66:67], 3, s[2:3]
	s_mov_b32 s18, 0
	v_mov_b32_e32 v0, 0
	v_mov_b32_e32 v1, v149
	v_mov_b32_e32 v2, v149
	v_mov_b32_e32 v3, v149
	v_mov_b32_e32 v4, v149
	v_mov_b32_e32 v5, v149
	v_mov_b32_e32 v6, v149
	v_mov_b32_e32 v7, v149
	v_mov_b32_e32 v8, v149
	v_mov_b32_e32 v9, v149
	v_mov_b32_e32 v10, v149
	v_mov_b32_e32 v11, v149
	v_mov_b32_e32 v12, v149
	v_mov_b32_e32 v13, v149
	v_mov_b32_e32 v14, v149
	v_mov_b32_e32 v15, v149
	v_mov_b32_e32 v16, 0
	v_mov_b32_e32 v17, v149
	v_mov_b32_e32 v18, v149
	v_mov_b32_e32 v19, v149
	v_mov_b32_e32 v20, v149
	v_mov_b32_e32 v21, v149
	v_mov_b32_e32 v22, v149
	v_mov_b32_e32 v23, v149
	v_mov_b32_e32 v24, v149
	v_mov_b32_e32 v25, v149
	v_mov_b32_e32 v26, v149
	v_mov_b32_e32 v27, v149
	v_mov_b32_e32 v28, v149
	v_mov_b32_e32 v29, v149
	v_mov_b32_e32 v30, v149
	v_mov_b32_e32 v31, v149
	v_mov_b32_e32 v32, 0
	v_mov_b32_e32 v33, v149
	v_mov_b32_e32 v34, v149
	v_mov_b32_e32 v35, v149
	v_mov_b32_e32 v36, v149
	v_mov_b32_e32 v37, v149
	v_mov_b32_e32 v38, v149
	v_mov_b32_e32 v39, v149
	v_mov_b32_e32 v40, v149
	v_mov_b32_e32 v41, v149
	v_mov_b32_e32 v42, v149
	v_mov_b32_e32 v43, v149
	v_mov_b32_e32 v44, v149
	v_mov_b32_e32 v45, v149
	v_mov_b32_e32 v46, v149
	v_mov_b32_e32 v47, v149
	v_mov_b32_e32 v48, 0
	v_mov_b32_e32 v49, v149
	v_mov_b32_e32 v50, v149
	v_mov_b32_e32 v51, v149
	v_mov_b32_e32 v52, v149
	v_mov_b32_e32 v53, v149
	v_mov_b32_e32 v54, v149
	v_mov_b32_e32 v55, v149
	v_mov_b32_e32 v56, v149
	v_mov_b32_e32 v57, v149
	v_mov_b32_e32 v58, v149
	v_mov_b32_e32 v59, v149
	v_mov_b32_e32 v60, v149
	v_mov_b32_e32 v61, v149
	v_mov_b32_e32 v62, v149
	v_mov_b32_e32 v63, v149
	s_waitcnt vmcnt(0)
	v_mov_b64_e32 v[174:175], v[176:177]
	v_readfirstlane_b32 s20, v186
	s_mov_b32 s21, 0
	s_mov_b32 s23, 0x8800
	s_mov_b32 s24, 0x11000
	s_bfe_u32 s20, s20, 0x10008
	s_cmp_eq_u32 s20, 0
	s_cbranch_scc1 .Lat_top
	s_mov_b32 s2, 0xffff8000
	s_mov_b32 s3, -1
	v_lshl_add_u64 v[172:173], v[172:173], 0, s[2:3]
	.p2align 6
	s_nop 0
	s_nop 0
	s_nop 0
	s_nop 0
	s_nop 0
	s_nop 0
